# trim stack: v59 + attention VALU trims + hand-written short-conv branch + P7 instruction trims (all region-verified)
# speedup vs baseline: 1.0032x; 1.0032x over previous
; #define LAS __attribute__((address_space(3)))
; __device__ __forceinline__ void attn_phase(const bf16* __restrict__ proj, const bf16* __restrict__ vt, bf16* __restrict__ ya, const float* __restrict__ rpb, int T, int vcu, int G, LAS unsigned char* lds) {
;     ...
;                 for (int j = 0; j < 4; ++j) { const int kr = ka - rsj[j];
;                     if (kr >= 0 && kr < 8) {
;                         f32x4 st[2];
; #pragma unroll
;                         for (int hf = 0; hf < 2; ++hf) { const f32x4 t = __builtin_amdgcn_mfma_f32_16x16x32_bf16(kf[hf][0], qf[j][0], (f32x4){0.f, 0.f, 0.f, 0.f}, 0, 0, 0);
;                             st[hf] = __builtin_amdgcn_mfma_f32_16x16x32_bf16(kf[hf][1], qf[j][1], t, 0, 0, 0); }
;                         const LAS float* tb = tbh + (ka - i0 - j + 7) * 31;
;                         float mloc = -INFINITY;
; #pragma unroll
;                         for (int hf = 0; hf < 2; ++hf)
; #pragma unroll
;                             for (int e = 0; e < 4; ++e) { const unsigned dc = ((hf == 0 ? dpack0 : dpack1) >> (8 * e)) & 0xffu; const float b = tb[dc];
;                                 const float v = ((vmask >> (hf * 4 + e)) & 1u) ? st[hf][e] * SC + b : -INFINITY; st[hf][e] = v; mloc = fmaxf(mloc, v); }
;                         mloc = fmaxf(mloc, __shfl_xor(mloc, 16)); mloc = fmaxf(mloc, __shfl_xor(mloc, 32));
;                         const float mnew = fmaxf(mrun[j], mloc), alpha = __builtin_amdgcn_exp2f(mrun[j] - mnew); mrun[j] = mnew;
;                         float p[8], psum = 0.f;
; #pragma unroll
;                         for (int hf = 0; hf < 2; ++hf)
; #pragma unroll
;                             for (int e = 0; e < 4; ++e) { p[hf * 4 + e] = __builtin_amdgcn_exp2f(st[hf][e] - mnew); psum += p[hf * 4 + e]; }
;                         lrun[j] = lrun[j] * alpha + psum;
;                         v4u w; w.x = cvt_pk_bf16(p[0], p[1]); w.y = cvt_pk_bf16(p[2], p[3]); w.z = cvt_pk_bf16(p[4], p[5]); w.w = cvt_pk_bf16(p[6], p[7]);
;                         const bf16x8 pk = __builtin_bit_cast(bf16x8, w);
; #pragma unroll
;                         for (int dt = 0; dt < 4; ++dt) o[j][dt] = __builtin_amdgcn_mfma_f32_16x16x32_bf16(__builtin_bit_cast(bf16x8, vf[dt]), pk, o[j][dt] * alpha, 0, 0, 0);
;                     } }
.LBB0_485:
	ds_read_b32 v251, v237
	ds_read_b32 v250, v236
	ds_read_b32 v227, v235
	ds_read_b32 v226, v234
	ds_read_b32 v199, v233
	ds_read_b32 v212, v221
	ds_read_b32 v213, v220
	ds_read_b32 v214, v219
	s_waitcnt vmcnt(15)
	v_mfma_f32_16x16x32_bf16 v[146:149], v[118:121], v[66:69], 0
	s_waitcnt vmcnt(14)
	v_mfma_f32_16x16x32_bf16 v[150:153], v[122:125], v[70:73], v[146:149]
	s_waitcnt vmcnt(12)
	v_mfma_f32_16x16x32_bf16 v[146:149], v[126:129], v[66:69], 0
	v_mfma_f32_16x16x32_bf16 v[146:149], v[110:113], v[70:73], v[146:149]
	s_nop 7
	s_waitcnt lgkmcnt(0)
	v_fmamk_f32 v150, v150, 0x3e38aa3b, v251
	v_fmamk_f32 v151, v151, 0x3e38aa3b, v250
	v_fmamk_f32 v152, v152, 0x3e38aa3b, v227
	v_fmamk_f32 v153, v153, 0x3e38aa3b, v226
	v_fmamk_f32 v146, v146, 0x3e38aa3b, v199
	v_fmamk_f32 v147, v147, 0x3e38aa3b, v212
	v_fmamk_f32 v148, v148, 0x3e38aa3b, v213
	v_fmamk_f32 v149, v149, 0x3e38aa3b, v214
	v_max3_f32 v225, v150, v151, v152
	v_max3_f32 v225, v225, v153, v146
	v_max3_f32 v225, v225, v147, v148
	v_max_f32_e32 v225, v225, v149
	v_mov_b32_e32 v226, v225
	s_nop 1
	v_permlane16_swap_b32_e32 v225, v226
	v_max_f32_e32 v225, v225, v226
	v_mov_b32_e32 v226, v225
	s_nop 1
	v_permlane32_swap_b32_e32 v225, v226
	v_max3_f32 v225, v249, v225, v226
	v_sub_f32_e32 v250, v249, v225
	v_sub_f32_e32 v150, v150, v225
	v_sub_f32_e32 v151, v151, v225
	v_sub_f32_e32 v152, v152, v225
	v_sub_f32_e32 v153, v153, v225
	v_sub_f32_e32 v146, v146, v225
	v_sub_f32_e32 v147, v147, v225
	v_sub_f32_e32 v148, v148, v225
	v_sub_f32_e32 v149, v149, v225
	v_exp_f32_e32 v250, v250
	v_exp_f32_e32 v150, v150
	v_exp_f32_e32 v151, v151
	v_exp_f32_e32 v152, v152
	v_exp_f32_e32 v153, v153
	v_exp_f32_e32 v146, v146
	v_exp_f32_e32 v147, v147
	v_exp_f32_e32 v148, v148
	v_exp_f32_e32 v149, v149
	v_mov_b32_e32 v249, v225
	v_add_f32_e32 v226, v150, v151
	v_add_f32_e32 v226, v226, v152
	v_add_f32_e32 v226, v226, v153
	v_add_f32_e32 v226, v226, v146
	v_add_f32_e32 v226, v226, v147
	v_add_f32_e32 v226, v226, v148
	v_add_f32_e32 v226, v226, v149
	v_fma_f32 v218, v218, v250, v226
	v_pk_mul_f32 v[64:65], v[64:65], v[250:251] op_sel_hi:[1,0]
	v_pk_mul_f32 v[62:63], v[62:63], v[250:251] op_sel_hi:[1,0]
	v_pk_mul_f32 v[60:61], v[60:61], v[250:251] op_sel_hi:[1,0]
	v_pk_mul_f32 v[58:59], v[58:59], v[250:251] op_sel_hi:[1,0]
	v_pk_mul_f32 v[56:57], v[56:57], v[250:251] op_sel_hi:[1,0]
	v_pk_mul_f32 v[54:55], v[54:55], v[250:251] op_sel_hi:[1,0]
	v_pk_mul_f32 v[52:53], v[52:53], v[250:251] op_sel_hi:[1,0]
	v_pk_mul_f32 v[50:51], v[50:51], v[250:251] op_sel_hi:[1,0]
	v_cvt_pk_bf16_f32 v150, v150, v151
	v_cvt_pk_bf16_f32 v151, v152, v153
	v_cvt_pk_bf16_f32 v152, v146, v147
	v_cvt_pk_bf16_f32 v153, v148, v149
	s_nop 1
	s_waitcnt vmcnt(11)
	v_mfma_f32_16x16x32_bf16 v[62:65], v[142:145], v[150:153], v[62:65]
	s_waitcnt vmcnt(10)
	v_mfma_f32_16x16x32_bf16 v[58:61], v[134:137], v[150:153], v[58:61]
	s_waitcnt vmcnt(9)
	v_mfma_f32_16x16x32_bf16 v[54:57], v[138:141], v[150:153], v[54:57]
	s_waitcnt vmcnt(8)
	v_mfma_f32_16x16x32_bf16 v[50:53], v[130:133], v[150:153], v[50:53]

; #define LAS __attribute__((address_space(3)))
; __device__ __forceinline__ void attn_phase(const bf16* __restrict__ proj, const bf16* __restrict__ vt, bf16* __restrict__ ya, const float* __restrict__ rpb, int T, int vcu, int G, LAS unsigned char* lds) {
;     ...
;                 for (int j = 0; j < 4; ++j) { const int kr = ka - rsj[j];
;                     if (kr >= 0 && kr < 8) {
;                         f32x4 st[2];
; #pragma unroll
;                         for (int hf = 0; hf < 2; ++hf) { const f32x4 t = __builtin_amdgcn_mfma_f32_16x16x32_bf16(kf[hf][0], qf[j][0], (f32x4){0.f, 0.f, 0.f, 0.f}, 0, 0, 0);
;                             st[hf] = __builtin_amdgcn_mfma_f32_16x16x32_bf16(kf[hf][1], qf[j][1], t, 0, 0, 0); }
;                         const LAS float* tb = tbh + (ka - i0 - j + 7) * 31;
;                         float mloc = -INFINITY;
; #pragma unroll
;                         for (int hf = 0; hf < 2; ++hf)
; #pragma unroll
;                             for (int e = 0; e < 4; ++e) { const unsigned dc = ((hf == 0 ? dpack0 : dpack1) >> (8 * e)) & 0xffu; const float b = tb[dc];
;                                 const float v = ((vmask >> (hf * 4 + e)) & 1u) ? st[hf][e] * SC + b : -INFINITY; st[hf][e] = v; mloc = fmaxf(mloc, v); }
;                         mloc = fmaxf(mloc, __shfl_xor(mloc, 16)); mloc = fmaxf(mloc, __shfl_xor(mloc, 32));
;                         const float mnew = fmaxf(mrun[j], mloc), alpha = __builtin_amdgcn_exp2f(mrun[j] - mnew); mrun[j] = mnew;
;                         float p[8], psum = 0.f;
; #pragma unroll
;                         for (int hf = 0; hf < 2; ++hf)
; #pragma unroll
;                             for (int e = 0; e < 4; ++e) { p[hf * 4 + e] = __builtin_amdgcn_exp2f(st[hf][e] - mnew); psum += p[hf * 4 + e]; }
;                         lrun[j] = lrun[j] * alpha + psum;
;                         v4u w; w.x = cvt_pk_bf16(p[0], p[1]); w.y = cvt_pk_bf16(p[2], p[3]); w.z = cvt_pk_bf16(p[4], p[5]); w.w = cvt_pk_bf16(p[6], p[7]);
;                         const bf16x8 pk = __builtin_bit_cast(bf16x8, w);
; #pragma unroll
;                         for (int dt = 0; dt < 4; ++dt) o[j][dt] = __builtin_amdgcn_mfma_f32_16x16x32_bf16(__builtin_bit_cast(bf16x8, vf[dt]), pk, o[j][dt] * alpha, 0, 0, 0);
;                     } }
.LBB0_505:
	ds_read_b32 v251, v245 offset:256
	ds_read_b32 v250, v244 offset:256
	ds_read_b32 v227, v243 offset:256
	ds_read_b32 v226, v242 offset:256
	ds_read_b32 v199, v241 offset:256
	ds_read_b32 v212, v240 offset:256
	ds_read_b32 v213, v239 offset:256
	ds_read_b32 v214, v238 offset:256
	s_waitcnt vmcnt(15)
	v_mfma_f32_16x16x32_bf16 v[146:149], v[118:121], v[74:77], 0
	s_waitcnt vmcnt(14)
	v_mfma_f32_16x16x32_bf16 v[150:153], v[122:125], v[78:81], v[146:149]
	s_waitcnt vmcnt(12)
	v_mfma_f32_16x16x32_bf16 v[146:149], v[126:129], v[74:77], 0
	v_mfma_f32_16x16x32_bf16 v[146:149], v[110:113], v[78:81], v[146:149]
	s_nop 7
	s_waitcnt lgkmcnt(0)
	v_fmamk_f32 v150, v150, 0x3e38aa3b, v251
	v_fmamk_f32 v151, v151, 0x3e38aa3b, v250
	v_fmamk_f32 v152, v152, 0x3e38aa3b, v227
	v_fmamk_f32 v153, v153, 0x3e38aa3b, v226
	v_fmamk_f32 v146, v146, 0x3e38aa3b, v199
	v_fmamk_f32 v147, v147, 0x3e38aa3b, v212
	v_fmamk_f32 v148, v148, 0x3e38aa3b, v213
	v_fmamk_f32 v149, v149, 0x3e38aa3b, v214
	v_max3_f32 v225, v150, v151, v152
	v_max3_f32 v225, v225, v153, v146
	v_max3_f32 v225, v225, v147, v148
	v_max_f32_e32 v225, v225, v149
	v_mov_b32_e32 v226, v225
	s_nop 1
	v_permlane16_swap_b32_e32 v225, v226
	v_max_f32_e32 v225, v225, v226
	v_mov_b32_e32 v226, v225
	s_nop 1
	v_permlane32_swap_b32_e32 v225, v226
	v_max3_f32 v225, v248, v225, v226
	v_sub_f32_e32 v250, v248, v225
	v_sub_f32_e32 v150, v150, v225
	v_sub_f32_e32 v151, v151, v225
	v_sub_f32_e32 v152, v152, v225
	v_sub_f32_e32 v153, v153, v225
	v_sub_f32_e32 v146, v146, v225
	v_sub_f32_e32 v147, v147, v225
	v_sub_f32_e32 v148, v148, v225
	v_sub_f32_e32 v149, v149, v225
	v_exp_f32_e32 v250, v250
	v_exp_f32_e32 v150, v150
	v_exp_f32_e32 v151, v151
	v_exp_f32_e32 v152, v152
	v_exp_f32_e32 v153, v153
	v_exp_f32_e32 v146, v146
	v_exp_f32_e32 v147, v147
	v_exp_f32_e32 v148, v148
	v_exp_f32_e32 v149, v149
	v_mov_b32_e32 v248, v225
	v_add_f32_e32 v226, v150, v151
	v_add_f32_e32 v226, v226, v152
	v_add_f32_e32 v226, v226, v153
	v_add_f32_e32 v226, v226, v146
	v_add_f32_e32 v226, v226, v147
	v_add_f32_e32 v226, v226, v148
	v_add_f32_e32 v226, v226, v149
	v_fma_f32 v217, v217, v250, v226
	v_pk_mul_f32 v[48:49], v[48:49], v[250:251] op_sel_hi:[1,0]
	v_pk_mul_f32 v[46:47], v[46:47], v[250:251] op_sel_hi:[1,0]
	v_pk_mul_f32 v[44:45], v[44:45], v[250:251] op_sel_hi:[1,0]
	v_pk_mul_f32 v[42:43], v[42:43], v[250:251] op_sel_hi:[1,0]
	v_pk_mul_f32 v[40:41], v[40:41], v[250:251] op_sel_hi:[1,0]
	v_pk_mul_f32 v[38:39], v[38:39], v[250:251] op_sel_hi:[1,0]
	v_pk_mul_f32 v[36:37], v[36:37], v[250:251] op_sel_hi:[1,0]
	v_pk_mul_f32 v[34:35], v[34:35], v[250:251] op_sel_hi:[1,0]
	v_cvt_pk_bf16_f32 v150, v150, v151
	v_cvt_pk_bf16_f32 v151, v152, v153
	v_cvt_pk_bf16_f32 v152, v146, v147
	v_cvt_pk_bf16_f32 v153, v148, v149
	s_nop 1
	s_waitcnt vmcnt(11)
	v_mfma_f32_16x16x32_bf16 v[46:49], v[142:145], v[150:153], v[46:49]
	s_waitcnt vmcnt(10)
	v_mfma_f32_16x16x32_bf16 v[42:45], v[134:137], v[150:153], v[42:45]
	s_waitcnt vmcnt(9)
	v_mfma_f32_16x16x32_bf16 v[38:41], v[138:141], v[150:153], v[38:41]
	s_waitcnt vmcnt(8)
	v_mfma_f32_16x16x32_bf16 v[34:37], v[130:133], v[150:153], v[34:37]
	s_add_i32 s24, s93, s90
	s_cmp_gt_u32 s24, 7
	s_cbranch_scc1 .LBB0_504
; #define LAS __attribute__((address_space(3)))
; __device__ __forceinline__ void attn_phase(const bf16* __restrict__ proj, const bf16* __restrict__ vt, bf16* __restrict__ ya, const float* __restrict__ rpb, int T, int vcu, int G, LAS unsigned char* lds) {
;     ...
;                 for (int j = 0; j < 4; ++j) { const int kr = ka - rsj[j];
;                     if (kr >= 0 && kr < 8) {
;                         f32x4 st[2];
; #pragma unroll
;                         for (int hf = 0; hf < 2; ++hf) { const f32x4 t = __builtin_amdgcn_mfma_f32_16x16x32_bf16(kf[hf][0], qf[j][0], (f32x4){0.f, 0.f, 0.f, 0.f}, 0, 0, 0);
;                             st[hf] = __builtin_amdgcn_mfma_f32_16x16x32_bf16(kf[hf][1], qf[j][1], t, 0, 0, 0); }
;                         const LAS float* tb = tbh + (ka - i0 - j + 7) * 31;
;                         float mloc = -INFINITY;
; #pragma unroll
;                         for (int hf = 0; hf < 2; ++hf)
; #pragma unroll
;                             for (int e = 0; e < 4; ++e) { const unsigned dc = ((hf == 0 ? dpack0 : dpack1) >> (8 * e)) & 0xffu; const float b = tb[dc];
;                                 const float v = ((vmask >> (hf * 4 + e)) & 1u) ? st[hf][e] * SC + b : -INFINITY; st[hf][e] = v; mloc = fmaxf(mloc, v); }
;                         mloc = fmaxf(mloc, __shfl_xor(mloc, 16)); mloc = fmaxf(mloc, __shfl_xor(mloc, 32));
;                         const float mnew = fmaxf(mrun[j], mloc), alpha = __builtin_amdgcn_exp2f(mrun[j] - mnew); mrun[j] = mnew;
;                         float p[8], psum = 0.f;
; #pragma unroll
;                         for (int hf = 0; hf < 2; ++hf)
; #pragma unroll
;                             for (int e = 0; e < 4; ++e) { p[hf * 4 + e] = __builtin_amdgcn_exp2f(st[hf][e] - mnew); psum += p[hf * 4 + e]; }
;                         lrun[j] = lrun[j] * alpha + psum;
;                         v4u w; w.x = cvt_pk_bf16(p[0], p[1]); w.y = cvt_pk_bf16(p[2], p[3]); w.z = cvt_pk_bf16(p[4], p[5]); w.w = cvt_pk_bf16(p[6], p[7]);
;                         const bf16x8 pk = __builtin_bit_cast(bf16x8, w);
; #pragma unroll
;                         for (int dt = 0; dt < 4; ++dt) o[j][dt] = __builtin_amdgcn_mfma_f32_16x16x32_bf16(__builtin_bit_cast(bf16x8, vf[dt]), pk, o[j][dt] * alpha, 0, 0, 0);
;                     } }
.LBB0_522:
	ds_read_b32 v251, v245 offset:128
	ds_read_b32 v250, v244 offset:128
	ds_read_b32 v227, v243 offset:128
	ds_read_b32 v226, v242 offset:128
	ds_read_b32 v199, v241 offset:128
	ds_read_b32 v212, v240 offset:128
	ds_read_b32 v213, v239 offset:128
	ds_read_b32 v214, v238 offset:128
	s_waitcnt vmcnt(15)
	v_mfma_f32_16x16x32_bf16 v[146:149], v[118:121], v[82:85], 0
	s_waitcnt vmcnt(14)
	v_mfma_f32_16x16x32_bf16 v[150:153], v[122:125], v[86:89], v[146:149]
	s_waitcnt vmcnt(12)
	v_mfma_f32_16x16x32_bf16 v[146:149], v[126:129], v[82:85], 0
	v_mfma_f32_16x16x32_bf16 v[146:149], v[110:113], v[86:89], v[146:149]
	s_nop 7
	s_waitcnt lgkmcnt(0)
	v_fmamk_f32 v150, v150, 0x3e38aa3b, v251
	v_fmamk_f32 v151, v151, 0x3e38aa3b, v250
	v_fmamk_f32 v152, v152, 0x3e38aa3b, v227
	v_fmamk_f32 v153, v153, 0x3e38aa3b, v226
	v_fmamk_f32 v146, v146, 0x3e38aa3b, v199
	v_fmamk_f32 v147, v147, 0x3e38aa3b, v212
	v_fmamk_f32 v148, v148, 0x3e38aa3b, v213
	v_fmamk_f32 v149, v149, 0x3e38aa3b, v214
	v_max3_f32 v225, v150, v151, v152
	v_max3_f32 v225, v225, v153, v146
	v_max3_f32 v225, v225, v147, v148
	v_max_f32_e32 v225, v225, v149
	v_mov_b32_e32 v226, v225
	s_nop 1
	v_permlane16_swap_b32_e32 v225, v226
	v_max_f32_e32 v225, v225, v226
	v_mov_b32_e32 v226, v225
	s_nop 1
	v_permlane32_swap_b32_e32 v225, v226
	v_max3_f32 v225, v247, v225, v226
	v_sub_f32_e32 v250, v247, v225
	v_sub_f32_e32 v150, v150, v225
	v_sub_f32_e32 v151, v151, v225
	v_sub_f32_e32 v152, v152, v225
	v_sub_f32_e32 v153, v153, v225
	v_sub_f32_e32 v146, v146, v225
	v_sub_f32_e32 v147, v147, v225
	v_sub_f32_e32 v148, v148, v225
	v_sub_f32_e32 v149, v149, v225
	v_exp_f32_e32 v250, v250
	v_exp_f32_e32 v150, v150
	v_exp_f32_e32 v151, v151
	v_exp_f32_e32 v152, v152
	v_exp_f32_e32 v153, v153
	v_exp_f32_e32 v146, v146
	v_exp_f32_e32 v147, v147
	v_exp_f32_e32 v148, v148
	v_exp_f32_e32 v149, v149
	v_mov_b32_e32 v247, v225
	v_add_f32_e32 v226, v150, v151
	v_add_f32_e32 v226, v226, v152
	v_add_f32_e32 v226, v226, v153
	v_add_f32_e32 v226, v226, v146
	v_add_f32_e32 v226, v226, v147
	v_add_f32_e32 v226, v226, v148
	v_add_f32_e32 v226, v226, v149
	v_fma_f32 v216, v216, v250, v226
	v_pk_mul_f32 v[32:33], v[32:33], v[250:251] op_sel_hi:[1,0]
	v_pk_mul_f32 v[30:31], v[30:31], v[250:251] op_sel_hi:[1,0]
	v_pk_mul_f32 v[28:29], v[28:29], v[250:251] op_sel_hi:[1,0]
	v_pk_mul_f32 v[26:27], v[26:27], v[250:251] op_sel_hi:[1,0]
	v_pk_mul_f32 v[24:25], v[24:25], v[250:251] op_sel_hi:[1,0]
	v_pk_mul_f32 v[22:23], v[22:23], v[250:251] op_sel_hi:[1,0]
	v_pk_mul_f32 v[20:21], v[20:21], v[250:251] op_sel_hi:[1,0]
	v_pk_mul_f32 v[18:19], v[18:19], v[250:251] op_sel_hi:[1,0]
	v_cvt_pk_bf16_f32 v150, v150, v151
	v_cvt_pk_bf16_f32 v151, v152, v153
	v_cvt_pk_bf16_f32 v152, v146, v147
	v_cvt_pk_bf16_f32 v153, v148, v149
	s_nop 1
	s_waitcnt vmcnt(11)
	v_mfma_f32_16x16x32_bf16 v[30:33], v[142:145], v[150:153], v[30:33]
	s_waitcnt vmcnt(10)
	v_mfma_f32_16x16x32_bf16 v[26:29], v[134:137], v[150:153], v[26:29]
	s_waitcnt vmcnt(9)
	v_mfma_f32_16x16x32_bf16 v[22:25], v[138:141], v[150:153], v[22:25]
	s_waitcnt vmcnt(8)
	v_mfma_f32_16x16x32_bf16 v[18:21], v[130:133], v[150:153], v[18:21]
	s_add_i32 s24, s92, s90
	s_cmp_gt_u32 s24, 7
	s_cbranch_scc1 .LBB0_556
.LBB0_539:
	ds_read_b32 v251, v245
	ds_read_b32 v250, v244
	ds_read_b32 v227, v243
	ds_read_b32 v226, v242
	ds_read_b32 v199, v241
	ds_read_b32 v212, v240
	ds_read_b32 v213, v239
	ds_read_b32 v214, v238
	s_waitcnt vmcnt(15)
	v_mfma_f32_16x16x32_bf16 v[118:121], v[118:121], v[90:93], 0
	s_waitcnt vmcnt(14)
	v_mfma_f32_16x16x32_bf16 v[118:121], v[122:125], v[94:97], v[118:121]
	s_waitcnt vmcnt(12)
	v_mfma_f32_16x16x32_bf16 v[124:127], v[126:129], v[90:93], 0
	v_mfma_f32_16x16x32_bf16 v[110:113], v[110:113], v[94:97], v[124:127]
	s_nop 7
	s_waitcnt lgkmcnt(0)
	v_fmamk_f32 v118, v118, 0x3e38aa3b, v251
	v_fmamk_f32 v119, v119, 0x3e38aa3b, v250
	v_fmamk_f32 v120, v120, 0x3e38aa3b, v227
	v_fmamk_f32 v121, v121, 0x3e38aa3b, v226
	v_fmamk_f32 v110, v110, 0x3e38aa3b, v199
	v_fmamk_f32 v111, v111, 0x3e38aa3b, v212
	v_fmamk_f32 v112, v112, 0x3e38aa3b, v213
	v_fmamk_f32 v113, v113, 0x3e38aa3b, v214
	v_max3_f32 v225, v118, v119, v120
	v_max3_f32 v225, v225, v121, v110
	v_max3_f32 v225, v225, v111, v112
	v_max_f32_e32 v225, v225, v113
	v_mov_b32_e32 v226, v225
	s_nop 1
	v_permlane16_swap_b32_e32 v225, v226
	v_max_f32_e32 v225, v225, v226
	v_mov_b32_e32 v226, v225
	s_nop 1
	v_permlane32_swap_b32_e32 v225, v226
	v_max3_f32 v225, v246, v225, v226
	v_sub_f32_e32 v250, v246, v225
	v_sub_f32_e32 v118, v118, v225
	v_sub_f32_e32 v119, v119, v225
	v_sub_f32_e32 v120, v120, v225
	v_sub_f32_e32 v121, v121, v225
	v_sub_f32_e32 v110, v110, v225
	v_sub_f32_e32 v111, v111, v225
	v_sub_f32_e32 v112, v112, v225
	v_sub_f32_e32 v113, v113, v225
	v_exp_f32_e32 v250, v250
	v_exp_f32_e32 v118, v118
	v_exp_f32_e32 v119, v119
	v_exp_f32_e32 v120, v120
	v_exp_f32_e32 v121, v121
	v_exp_f32_e32 v110, v110
	v_exp_f32_e32 v111, v111
	v_exp_f32_e32 v112, v112
	v_exp_f32_e32 v113, v113
	v_mov_b32_e32 v246, v225
	v_add_f32_e32 v226, v118, v119
	v_add_f32_e32 v226, v226, v120
	v_add_f32_e32 v226, v226, v121
	v_add_f32_e32 v226, v226, v110
	v_add_f32_e32 v226, v226, v111
	v_add_f32_e32 v226, v226, v112
	v_add_f32_e32 v226, v226, v113
	v_fma_f32 v215, v215, v250, v226
	v_pk_mul_f32 v[16:17], v[16:17], v[250:251] op_sel_hi:[1,0]
	v_pk_mul_f32 v[14:15], v[14:15], v[250:251] op_sel_hi:[1,0]
	v_pk_mul_f32 v[12:13], v[12:13], v[250:251] op_sel_hi:[1,0]
	v_pk_mul_f32 v[10:11], v[10:11], v[250:251] op_sel_hi:[1,0]
	v_pk_mul_f32 v[8:9], v[8:9], v[250:251] op_sel_hi:[1,0]
	v_pk_mul_f32 v[6:7], v[6:7], v[250:251] op_sel_hi:[1,0]
	v_pk_mul_f32 v[4:5], v[4:5], v[250:251] op_sel_hi:[1,0]
	v_pk_mul_f32 v[2:3], v[2:3], v[250:251] op_sel_hi:[1,0]
	v_cvt_pk_bf16_f32 v118, v118, v119
	v_cvt_pk_bf16_f32 v119, v120, v121
	v_cvt_pk_bf16_f32 v120, v110, v111
	v_cvt_pk_bf16_f32 v121, v112, v113
	s_nop 1
	s_waitcnt vmcnt(11)
	v_mfma_f32_16x16x32_bf16 v[14:17], v[142:145], v[118:121], v[14:17]
	s_waitcnt vmcnt(10)
	v_mfma_f32_16x16x32_bf16 v[10:13], v[134:137], v[118:121], v[10:13]
	s_waitcnt vmcnt(9)
	v_mfma_f32_16x16x32_bf16 v[6:9], v[138:141], v[118:121], v[6:9]
	s_waitcnt vmcnt(8)
	v_mfma_f32_16x16x32_bf16 v[2:5], v[130:133], v[118:121], v[2:5]
